# stack1 + attention unit loops: kernarg pointer loads hoisted out of MLA/FoX unit loops, no vmcnt(0) drain of previous unit's stores
# baseline (speedup 1.0000x reference)
; template <int MODE>
; __device__ __forceinline__ void attn_unit(const Params& P, int b, int h, int qb, unsigned char* smem) {
;     ...
;     Q = P.Qb + (size_t)b * SEQ * 768 + h * 96; ldq = 768; K = P.Kn + (size_t)b * SEQ * 512 + h * 64; ldk = 512;
;     Kr = P.Kr + (size_t)b * SEQ * 32; Vt = P.Vtb + (size_t)(b * 8 + h) * 64 * SEQ; O = P.mix + (size_t)b * SEQ * 1024 + 512 + h * 64;
; __device__ __forceinline__ void phase_attn_even(const Params& P, unsigned char* smem) {
;   const int bid = blockIdx.x, G = gridDim.x;
;   for (int j = 0;; ++j) {
;     const int u = j * G + ((j & 1) ? (G - 1 - bid) : bid);
;     if (u >= 1024) break;
;     const int qb = 15 - (u >> 6), pr = u & 63;
;     attn_unit<0>(P, pr >> 3, pr & 7, qb, smem);
.LBB0_837:
	s_or_b64 exec, exec, s[46:47]
	s_not_b32 s6, s2
	s_add_i32 s53, s38, s6
	s_mov_b64 s[8:9], s[0:1]
	s_cmpk_gt_i32 s2, 0x3ff
	s_waitcnt lgkmcnt(0)
	s_barrier
	s_cbranch_scc1 .LBB0_880
	s_waitcnt vmcnt(0)
	v_mbcnt_lo_u32_b32 v0, -1, 0
	s_mov_b32 s11, 0
	v_mov_b64_e32 v[138:139], s[8:9]
	flat_load_dwordx2 v[240:241], v[138:139] offset:448
	flat_load_dwordx4 v[244:247], v[138:139] offset:488
	flat_load_dwordx4 v[248:251], v[138:139] offset:464
	s_waitcnt vmcnt(0) lgkmcnt(0)
	s_movk_i32 s20, 0x600
	v_mov_b32_e32 v1, 0
	s_movk_i32 s21, 0x70
	s_movk_i32 s22, 0x100
	s_mov_b64 s[12:13], 0x80
	s_mov_b64 s[14:15], 0x10000
	v_mov_b32_e32 v143, 0xff800000
	v_mbcnt_hi_u32_b32 v147, -1, v0
	s_mov_b32 s6, s2
	s_mov_b32 s23, 0
	s_branch .LBB0_840

; #define GAS __attribute__((address_space(1)))
; template <int MODE>
; __device__ __forceinline__ void attn_unit(const Params& P, int b, int h, int qb, unsigned char* smem) {
;     ...
;     Q = P.Qb + (size_t)b * SEQ * 768 + h * 96; ldq = 768; K = P.Kn + (size_t)b * SEQ * 512 + h * 64; ldk = 512;
;     Kr = P.Kr + (size_t)b * SEQ * 32; Vt = P.Vtb + (size_t)(b * 8 + h) * 64 * SEQ; O = P.mix + (size_t)b * SEQ * 1024 + 512 + h * 64;
;   } else if (MODE == 1) {
;     Q = P.Qc + (size_t)b * SEQ * 1024 + h * 64; ldq = 1024; K = P.Kc + (size_t)b * SEQ * 1024 + h * 64; ldk = 1024;
;     Vt = P.Vtc + (size_t)(b * 16 + h) * 64 * SEQ; O = P.Qc + (size_t)b * SEQ * 1024 + h * 64; cb = P.logc + (size_t)(b * 16 + h) * SEQ;
;   } else {
;     Q = P.Qa + (size_t)b * SEQ * 512 + h * 64; ldq = 512; K = P.Ka + (size_t)b * SEQ * 128 + (h >> 2) * 64; ldk = 128;
;     Vt = P.Vta + (size_t)(b * 2 + (h >> 2)) * 64 * SEQ; O = P.mix + (size_t)b * SEQ * 1024 + h * 64;
;     slope2 = exp2f(-(float)(h + 1)) * LOG2E;
;     m_run = ((GAS const float*)P.ev_sinks)[h] * LOG2E; l_run = hi ? 0.f : 1.f;
;   }
;   const int q0 = qb * 256, qw0 = q0 + 32 * w, qi = qw0 + r;
;   bf16x8 qf[NKS];
; #pragma unroll
;   for (int ks = 0; ks < NKS; ++ks) qf[ks] = *(GAS const bf16x8*)(Q + (size_t)qi * ldq + 16 * ks + 8 * hi);
;     ...
;   auto gload = [&](int kt) {
;     const int k0 = kt * 64;
;     rk = *(GAS const u32x4*)(K + (size_t)(k0 + srow) * ldk + sch * 8);
;     rv = *(GAS const u32x4*)(Vt + (size_t)srow * SEQ + k0 + sch * 8);
;     if (MODE == 0) { if (tid < 256) rr_ = *(GAS const u32x4*)(Kr + (size_t)(k0 + rrow) * 32 + rch * 8); }
.LBB0_840:
	v_mov_b32_e32 v22, v254
	v_mov_b64_e32 v[6:7], v[240:241]
	v_mov_b64_e32 v[110:111], v[244:245]
	v_mov_b64_e32 v[112:113], v[246:247]
	v_mov_b64_e32 v[2:3], v[248:249]
	v_mov_b64_e32 v[4:5], v[250:251]
	s_ashr_i32 s26, s6, 6
	s_bfe_u32 s24, s6, 0x30003
	s_and_b32 s29, s6, 7
	v_ashrrev_i32_e32 v0, 1, v22
	s_sub_i32 s18, 15, s26
	s_mul_i32 s10, s24, 0x600000
	s_lshl_b32 s27, s24, 21
	s_lshl_b32 s28, s29, 18
	v_and_b32_e32 v8, 0xffffffe0, v0
	v_and_b32_e32 v24, 31, v22
	s_or_b32 s6, s27, s28
	v_lshl_add_u32 v146, s18, 8, v8
	s_mov_b32 s7, s11
	v_bfe_u32 v23, v22, 5, 1
	s_lshl_b32 s6, s6, 1
	v_or_b32_e32 v140, v146, v24
	v_lshlrev_b32_e32 v0, 4, v23
	v_ashrrev_i32_e32 v18, 3, v22
	s_mov_b32 s17, s11
	s_lshl_b32 s16, s29, 7
	v_ashrrev_i32_e32 v19, 31, v18
	v_lshlrev_b32_e32 v25, 4, v22
	v_lshlrev_b64 v[14:15], 10, v[18:19]
	v_lshlrev_b64 v[16:17], 13, v[18:19]
	v_bfe_u32 v19, v22, 2, 6
	s_waitcnt lgkmcnt(0)
	v_lshl_add_u64 v[6:7], v[6:7], 0, s[10:11]
	s_mul_i32 s10, s29, 0xc0
	v_lshl_add_u64 v[6:7], v[6:7], 0, s[10:11]
	v_lshl_add_u64 v[8:9], v[110:111], 0, s[6:7]
	v_mad_i64_i32 v[6:7], s[6:7], v140, s20, v[6:7]
	s_lshl_b32 s10, s24, 22
	v_lshl_add_u64 v[6:7], v[6:7], 0, v[0:1]
	v_lshl_add_u64 v[10:11], v[2:3], 0, s[10:11]
	global_load_dwordx4 v[118:121], v[6:7], off
	global_load_dwordx4 v[122:125], v[6:7], off offset:32
	global_load_dwordx4 v[126:129], v[6:7], off offset:64
	global_load_dwordx4 v[130:133], v[6:7], off offset:96
	global_load_dwordx4 v[134:137], v[6:7], off offset:128
	global_load_dwordx4 v[114:117], v[6:7], off offset:160
	v_lshl_add_u64 v[10:11], v[10:11], 0, s[16:17]
	v_and_b32_e32 v0, 0x70, v25
	v_lshl_add_u64 v[6:7], v[10:11], 0, v[14:15]
	v_lshl_add_u64 v[8:9], v[8:9], 0, v[16:17]
	v_lshl_add_u64 v[26:27], v[6:7], 0, v[0:1]
	v_lshl_add_u64 v[20:21], v[8:9], 0, v[0:1]
	global_load_dwordx4 v[6:9], v[26:27], off
	global_load_dwordx4 v[10:13], v[20:21], off
	s_lshl_b32 s6, s24, 18
	s_mov_b32 s7, s11
	v_and_b32_e32 v0, 3, v22
	v_lshl_add_u64 v[4:5], v[4:5], 0, s[6:7]
	v_lshlrev_b32_e32 v20, 6, v19
	v_cmp_gt_i32_e64 s[6:7], s22, v22
	v_lshlrev_b32_e32 v0, 4, v0
	s_and_saveexec_b64 s[18:19], s[6:7]
	s_cbranch_execz .LBB0_842
	v_mov_b32_e32 v21, v1
	v_lshl_add_u64 v[26:27], v[4:5], 0, v[20:21]
	v_lshl_add_u64 v[26:27], v[26:27], 0, v[0:1]
	global_load_dwordx4 v[80:83], v[26:27], off

; template <int MODE>
; __device__ __forceinline__ void attn_unit(const Params& P, int b, int h, int qb, unsigned char* smem) {
;     ...
;     Q = P.Qc + (size_t)b * SEQ * 1024 + h * 64; ldq = 1024; K = P.Kc + (size_t)b * SEQ * 1024 + h * 64; ldk = 1024;
;     Vt = P.Vtc + (size_t)(b * 16 + h) * 64 * SEQ; O = P.Qc + (size_t)b * SEQ * 1024 + h * 64; cb = P.logc + (size_t)(b * 16 + h) * SEQ;
; __device__ __forceinline__ void phase_attn_odd(const Params& P, unsigned char* smem) {
;   const int bid = blockIdx.x, G = gridDim.x;
;   for (int j = 0;; ++j) {
;     const int u = j * G + ((j & 1) ? (G - 1 - bid) : bid);
;     if (u >= 2048) break;
;     const int qb = 15 - (u >> 7), pr = u & 127;
;     attn_unit<1>(P, pr >> 4, pr & 15, qb, smem);
.LBB0_1607:
	s_or_b64 exec, exec, s[46:47]
	s_mov_b64 s[6:7], s[0:1]
	s_cmpk_gt_i32 s2, 0x7ff
	s_waitcnt lgkmcnt(0)
	s_barrier
	s_cbranch_scc1 .LBB0_1635
	v_mbcnt_lo_u32_b32 v0, -1, 0
	s_mov_b32 s9, 0
	v_mov_b64_e32 v[112:113], s[6:7]
	flat_load_dwordx4 v[230:233], v[112:113] offset:520
	flat_load_dwordx2 v[234:235], v[112:113] offset:536
	flat_load_dwordx2 v[236:237], v[112:113] offset:272
	s_waitcnt vmcnt(0) lgkmcnt(0)
	v_mov_b32_e32 v115, 0
	s_movk_i32 s22, 0x70
	s_mov_b64 s[10:11], 0x100
	s_mov_b64 s[12:13], 0x80
	s_mov_b64 s[14:15], 0x20000
	v_mov_b32_e32 v119, 0xff800000
	v_mbcnt_hi_u32_b32 v122, -1, v0
	s_mov_b32 s24, s2
	s_mov_b32 s23, 0
	s_branch .LBB0_1610

; #define GAS __attribute__((address_space(1)))
; template <int MODE>
; __device__ __forceinline__ void attn_unit(const Params& P, int b, int h, int qb, unsigned char* smem) {
;     ...
;     Q = P.Qc + (size_t)b * SEQ * 1024 + h * 64; ldq = 1024; K = P.Kc + (size_t)b * SEQ * 1024 + h * 64; ldk = 1024;
;     Vt = P.Vtc + (size_t)(b * 16 + h) * 64 * SEQ; O = P.Qc + (size_t)b * SEQ * 1024 + h * 64; cb = P.logc + (size_t)(b * 16 + h) * SEQ;
;   } else {
;     Q = P.Qa + (size_t)b * SEQ * 512 + h * 64; ldq = 512; K = P.Ka + (size_t)b * SEQ * 128 + (h >> 2) * 64; ldk = 128;
;     Vt = P.Vta + (size_t)(b * 2 + (h >> 2)) * 64 * SEQ; O = P.mix + (size_t)b * SEQ * 1024 + h * 64;
;     slope2 = exp2f(-(float)(h + 1)) * LOG2E;
;     m_run = ((GAS const float*)P.ev_sinks)[h] * LOG2E; l_run = hi ? 0.f : 1.f;
;   }
;   const int q0 = qb * 256, qw0 = q0 + 32 * w, qi = qw0 + r;
;   bf16x8 qf[NKS];
; #pragma unroll
;   for (int ks = 0; ks < NKS; ++ks) qf[ks] = *(GAS const bf16x8*)(Q + (size_t)qi * ldq + 16 * ks + 8 * hi);
;     ...
;   auto gload = [&](int kt) {
;     const int k0 = kt * 64;
;     rk = *(GAS const u32x4*)(K + (size_t)(k0 + srow) * ldk + sch * 8);
;     rv = *(GAS const u32x4*)(Vt + (size_t)srow * SEQ + k0 + sch * 8);
;     if (MODE == 0) { if (tid < 256) rr_ = *(GAS const u32x4*)(Kr + (size_t)(k0 + rrow) * 32 + rch * 8); }
;     if (MODE == 1) { if (tid < 16) rc = *(GAS const f32x4*)(cb + k0 + tid * 4); }
.LBB0_1610:
	v_mov_b32_e32 v22, v254
	v_mov_b64_e32 v[0:1], v[230:231]
	v_mov_b64_e32 v[2:3], v[232:233]
	v_mov_b64_e32 v[12:13], v[234:235]
	s_ashr_i32 s25, s24, 7
	v_ashrrev_i32_e32 v4, 1, v22
	s_sub_i32 s19, 15, s25
	v_and_b32_e32 v6, 0xffffffe0, v4
	s_lshl_b32 s6, s24, 19
	v_and_b32_e32 v24, 31, v22
	v_lshl_add_u32 v124, s19, 8, v6
	s_mov_b32 s17, s9
	s_lshl_b32 s8, s24, 7
	s_and_b32 s16, s6, 0x3800000
	v_or_b32_e32 v120, v124, v24
	s_mov_b32 s7, s9
	s_and_b32 s18, s24, 0x7f
	s_and_b32 s6, s8, 0x780
	v_ashrrev_i32_e32 v20, 3, v22
	v_ashrrev_i32_e32 v121, 31, v120
	s_lshl_b32 s8, s18, 19
	v_bfe_u32 v23, v22, 5, 1
	v_ashrrev_i32_e32 v21, 31, v20
	v_lshlrev_b64 v[6:7], 11, v[120:121]
	v_lshlrev_b32_e32 v82, 4, v22
	v_lshlrev_b32_e32 v114, 4, v23
	v_lshlrev_b64 v[14:15], 11, v[20:21]
	v_lshlrev_b64 v[18:19], 13, v[20:21]
	v_mov_b32_e32 v5, v115
	v_and_b32_e32 v4, 0x70, v82
	v_mov_b64_e32 v[16:17], v[236:237]
	s_lshl_b32 s18, s18, 14
	s_mov_b32 s19, s9
	s_waitcnt lgkmcnt(0)
	v_lshl_add_u64 v[0:1], v[0:1], 0, s[16:17]
	v_lshl_add_u64 v[8:9], v[2:3], 0, s[16:17]
	v_lshl_add_u64 v[0:1], v[0:1], 0, s[6:7]
	v_lshl_add_u64 v[10:11], v[12:13], 0, s[8:9]
	v_lshl_add_u64 v[8:9], v[8:9], 0, s[6:7]
	v_lshl_add_u64 v[116:117], v[0:1], 0, v[6:7]
	v_lshl_add_u64 v[10:11], v[10:11], 0, v[18:19]
	v_lshl_add_u64 v[0:1], v[8:9], 0, v[14:15]
	v_lshl_add_u64 v[28:29], v[116:117], 0, v[114:115]
	v_lshl_add_u64 v[26:27], v[10:11], 0, v[4:5]
	v_lshl_add_u64 v[0:1], v[0:1], 0, v[4:5]
	global_load_dwordx4 v[100:103], v[28:29], off
	global_load_dwordx4 v[104:107], v[28:29], off offset:32
	global_load_dwordx4 v[108:111], v[28:29], off offset:64
	global_load_dwordx4 v[96:99], v[28:29], off offset:96
	global_load_dwordx4 v[4:7], v[0:1], off
	global_load_dwordx4 v[8:11], v[26:27], off
	v_lshlrev_b32_e32 v0, 2, v22
	v_cmp_gt_i32_e64 s[6:7], 16, v22
	v_ashrrev_i32_e32 v1, 31, v0
	s_and_saveexec_b64 s[20:21], s[6:7]
	s_cbranch_execz .LBB0_1612
	v_lshl_add_u64 v[26:27], v[16:17], 0, s[18:19]
	v_lshl_add_u64 v[26:27], v[0:1], 2, v[26:27]
	global_load_dwordx4 v[64:67], v[26:27], off
